# GQA attention loop re-scheduled into separate vector / matrix phases for all waves (no role split there); MLA role split kept; hot loops page-contained
# baseline (speedup 1.0000x reference)
; __device__ __forceinline__ float xhalf_max(float m) { auto rr = __builtin_amdgcn_permlane32_swap(__float_as_uint(m), __float_as_uint(m), false, false); return fmaxf(__uint_as_float(rr[0]), __uint_as_float(rr[1])); }
; __device__ __forceinline__ float max3f(float a, float b, float c) { float r; asm("v_max3_f32 %0, %1, %2, %3" : "=v"(r) : "v"(a), "v"(b), "v"(c)); return r; }
; __device__ __forceinline__ float max2f(float a, float b) { float r; asm("v_max_f32_e32 %0, %1, %2" : "=v"(r) : "v"(a), "v"(b)); return r; }
; template <int GRP, bool has_next> __device__ __forceinline__ void att_step(const AttCtx<GRP>& C, AttState<GRP>& S, int s, f32x16& P0, f32x16& P1, f32x16& PN0, f32x16& PN1, u32x4& kreg, u32x4& preg, u32x4& vreg) {
;     ...
;     if ((t & 7) == 0) {
;         float ma = max3f(P0[0], P0[1], P0[2]), mb = max3f(P0[3], P0[4], P0[5]), mc = max3f(P1[0], P1[1], P1[2]), md = max3f(P1[3], P1[4], P1[5]);
;         ma = max3f(ma, P0[6], P0[7]); mb = max3f(mb, P0[8], P0[9]); mc = max3f(mc, P1[6], P1[7]); md = max3f(md, P1[8], P1[9]);
;         ma = max3f(ma, P0[10], P0[11]); mb = max3f(mb, P0[12], P0[13]); mc = max3f(mc, P1[10], P1[11]); md = max3f(md, P1[12], P1[13]);
;         ma = max3f(ma, P0[14], P0[15]); mc = max3f(mc, P1[14], P1[15]); ma = max3f(ma, mb, mc); mb = md;
;         const float mx = xhalf_max(max2f(ma, mb));
;         const int up = __any(mx > THR), dn = (t == 0) ? __any(mx < -THR) : 0;
; template <int GRP> ...
;     ...
;     if (wid >= 4) __builtin_amdgcn_s_setprio(1);
;     asm volatile("s_nop 15\n\ts_nop 7" : "+v"(pa0), "+v"(pa1));
;     for (int s = 0; s < NSTEP - 2; s += 2) { att_step<GRP, true>(C, S, s, pa0, pa1, pb0, pb1, kA, pA, vA); att_step<GRP, true>(C, S, s + 1, pb0, pb1, pa0, pa1, kA, pA, vA); }
.LBB0_807:
	v_lshlrev_b32_e32 v8, 3, v3
	v_mad_u32_u24 v10, v6, s37, v96
	v_lshlrev_b64 v[6:7], 11, v[132:133]
	v_mov_b32_e32 v9, v97
	v_mad_u64_u32 v[0:1], s[6:7], v0, s37, v[2:3]
	v_lshl_add_u64 v[134:135], s[48:49], 0, v[6:7]
	v_lshlrev_b32_e32 v96, 1, v8
	v_mov_b32_e32 v152, 0
	s_mov_b32 s62, 0
	v_cmp_eq_u32_e64 s[0:1], 0, v3
	v_lshlrev_b32_e32 v136, 2, v3
	v_lshl_add_u64 v[142:143], v[134:135], 0, v[8:9]
	v_lshl_add_u64 v[144:145], v[4:5], 0, v[96:97]
	v_add_u32_e32 v146, 0, v10
	v_add_u32_e32 v147, 0, v0
	v_mov_b32_e32 v137, 0
	s_mov_b32 s61, 0
	v_mov_b32_e32 v148, 0
	v_mov_b32_e32 v0, 0
	v_mov_b32_e32 v1, v152
	v_mov_b32_e32 v2, v152
	v_mov_b32_e32 v3, v152
	v_mov_b32_e32 v4, v152
	v_mov_b32_e32 v5, v152
	v_mov_b32_e32 v6, v152
	v_mov_b32_e32 v7, v152
	v_mov_b32_e32 v8, v152
	v_mov_b32_e32 v9, v152
	v_mov_b32_e32 v10, v152
	v_mov_b32_e32 v11, v152
	v_mov_b32_e32 v12, v152
	v_mov_b32_e32 v13, v152
	v_mov_b32_e32 v14, v152
	v_mov_b32_e32 v15, v152
	v_mov_b32_e32 v16, 0
	v_mov_b32_e32 v17, v152
	v_mov_b32_e32 v18, v152
	v_mov_b32_e32 v19, v152
	v_mov_b32_e32 v20, v152
	v_mov_b32_e32 v21, v152
	v_mov_b32_e32 v22, v152
	v_mov_b32_e32 v23, v152
	v_mov_b32_e32 v24, v152
	v_mov_b32_e32 v25, v152
	v_mov_b32_e32 v26, v152
	v_mov_b32_e32 v27, v152
	v_mov_b32_e32 v28, v152
	v_mov_b32_e32 v29, v152
	v_mov_b32_e32 v30, v152
	v_mov_b32_e32 v31, v152
	s_nop 15
	s_nop 7
	s_waitcnt lgkmcnt(0)
	s_barrier
	v_readfirstlane_b32 s93, v254
	s_cmpk_gt_u32 s93, 0xff
	s_branch .Lgqa_T_entry
	s_and_b32 s10, s61, 6
	s_cmp_lg_u32 s10, 0
	s_cbranch_scc1 .Lgqa_nomax1001
	v_max3_f32 v96, v48, v49, v50
	v_max3_f32 v99, v32, v33, v34
	v_max3_f32 v98, v51, v52, v53
	v_max3_f32 v153, v35, v36, v37
	s_and_b32 s10, s61, 56
	v_max3_f32 v96, v96, v54, v55
	v_max3_f32 v99, v99, v38, v39
	v_max3_f32 v98, v98, v56, v57
	v_max3_f32 v153, v153, v40, v41
	s_cmp_eq_u32 s10, 0
	v_max3_f32 v96, v96, v58, v59
	v_max3_f32 v99, v99, v42, v43
	v_max3_f32 v98, v98, v60, v61
	v_max3_f32 v153, v153, v44, v45
	s_cselect_b64 s[6:7], -1, 0
	v_max3_f32 v96, v96, v62, v63
	v_max3_f32 v99, v99, v46, v47
	s_cmp_lg_u32 s10, 0
	v_max3_f32 v96, v96, v98, v99
	s_nop 0
	v_max_f32_e32 v96, v96, v153
	s_nop 0
	v_mov_b32_e32 v98, v96
	s_nop 1
	v_permlane32_swap_b32_e32 v96, v98
	v_max_f32_e32 v98, v98, v98
	v_max_f32_e32 v96, v96, v96
	v_max_f32_e32 v96, v96, v98
	v_cmp_lt_f32_e32 vcc, s54, v96
	v_mov_b32_e32 v98, 0
	s_cbranch_scc1 .Lgqa_mx1002
	v_cmp_gt_f32_e64 s[10:11], s55, v96
	s_cmp_lg_u64 s[10:11], 0
	s_cselect_b64 s[10:11], -1, 0
	v_cndmask_b32_e64 v98, 0, 1, s[10:11]

; #define PG8_BAR __builtin_amdgcn_s_barrier()
; template <class Epi, class Sched, bool ALIGN_EPI = false, bool SP2 = false>
; __device__ __forceinline__ void gemm_phase(PG8_LAS unsigned char* lds, const Gemm g, const Sched S, const Epi E) {
;     ...
;         const bool has_next = S.next(ui + 1, nxt);
;         const char* nA = has_next ? (const char*)g.A + (size_t)nxt.pm * tstep : cA; const char* nB = has_next ? (const char*)g.Bt + (size_t)nxt.pn * tstep : cB;
;         for (int t = 0; t < nt; t += 2) {
;             if constexpr (Epi::MIDT >= 0) { if (t == Epi::MIDT) E.mid(acc, cur, wr, fr); }
;             const bool last = (t == nt - 2);
;             const char* a1 = cA + (size_t)(t + 1) * kstep;
;             const char* a2 = last ? nA : cA + (size_t)(t + 2) * kstep; const char* b2 = last ? nB : cB + (size_t)(t + 2) * kstep;
;             const char* a3 = a2 + kstep; const char* b3 = b2 + kstep;
;             if (last && has_next) S.a_ready(nxt);
;             if constexpr (SP2) {
;             PG8_LDB(B0, 0, 0); PG8_LDB(B1, 0, 1); PG8_SCHED; PG8_LDA(At, 0, 0); PG8_STAGE(PG8_SA(1, 1), a1 + hstep, voffA);
;             PG8_WAIT_V(8); PG8_WAIT_L(0); PG8_BAR; PG8_MMA(0, 0, At, B0); PG8_MMA(0, 1, At, B1); PG8_BAR; PG8_SCHED;
;             PG8_LDA(At, 0, 1); PG8_STAGE(PG8_SB(0, 0), b2, voffB); PG8_STAGE(PG8_SB(0, 1), b2 + hstep, voffB); PG8_STAGE(PG8_SA(0, 0), a2, voffA);
;             PG8_WAIT_V(8); PG8_WAIT_L(0); PG8_BAR; PG8_MMA(1, 0, At, B0); PG8_MMA(1, 1, At, B1); PG8_BAR; PG8_SCHED;
;             PG8_LDB(B0, 1, 0); PG8_LDB(B1, 1, 1); PG8_SCHED; PG8_LDA(At, 1, 0); PG8_STAGE(PG8_SA(0, 1), a2 + hstep, voffA);
;             PG8_WAIT_V(8); PG8_WAIT_L(0); PG8_BAR; PG8_MMA(0, 0, At, B0); PG8_MMA(0, 1, At, B1); PG8_BAR; PG8_SCHED;
;             PG8_LDA(At, 1, 1); PG8_STAGE(PG8_SB(1, 0), b3, voffB); PG8_STAGE(PG8_SB(1, 1), b3 + hstep, voffB); PG8_STAGE(PG8_SA(1, 0), a3, voffA);
;             PG8_WAIT_V(8); PG8_WAIT_L(0); PG8_BAR; PG8_MMA(1, 0, At, B0); PG8_MMA(1, 1, At, B1); PG8_BAR; PG8_SCHED;
;             } else {
;             PG8_LDB(B0, 0, 0); PG8_SCHED; PG8_LDA(At, 0, 0); PG8_STAGE(PG8_SA(1, 1), a1 + hstep, voffA);
;             PG8_WAIT_L(8); PG8_BAR; PG8_WAIT_L(0); PG8_MMA(0, 0, At, B0); PG8_BAR; PG8_SCHED;
;             PG8_LDB(B1, 0, 1); PG8_STAGE(PG8_SB(0, 0), b2, voffB);
;             PG8_BAR; PG8_WAIT_L(0); PG8_MMA(0, 1, At, B1); PG8_BAR;
.LBB0_897:
	s_ashr_i32 s51, s50, 31
	s_lshl_b64 s[10:11], s[50:51], 19
	s_add_u32 s52, s48, s10
	v_lshl_add_u32 v2, s64, 10, v171
	s_addc_u32 s53, s49, s11
	v_add_u32_e32 v4, 0x200, v2
	s_and_b64 s[10:11], s[0:1], exec
	v_ashrrev_i32_e32 v5, 31, v4
	s_cselect_b32 s51, s53, s67
	s_cselect_b32 s72, s52, s66
	s_ashr_i32 s45, s44, 31
	v_lshl_add_u64 v[130:131], v[4:5], 2, s[46:47]
	v_add_u32_e32 v4, 0x240, v2
	s_lshl_b64 s[10:11], s[44:45], 19
	v_readlane_b32 s14, v255, 34
	v_ashrrev_i32_e32 v3, 31, v2
	v_ashrrev_i32_e32 v5, 31, v4
	v_readlane_b32 s15, v255, 35
	s_add_u32 s62, s14, s10
	v_lshl_add_u64 v[128:129], v[2:3], 2, s[46:47]
	v_lshl_add_u64 v[132:133], v[4:5], 2, s[46:47]
	v_add_u32_e32 v4, 0x280, v2
	v_add_u32_e32 v2, 0x2c0, v2
	s_addc_u32 s63, s15, s11
	v_ashrrev_i32_e32 v3, 31, v2
	s_and_b64 s[10:11], s[0:1], exec
	v_ashrrev_i32_e32 v5, 31, v4
	v_lshl_add_u64 v[136:137], v[2:3], 2, s[46:47]
	v_mov_b32_e32 v2, v0
	v_mov_b32_e32 v3, v0
	s_cselect_b32 s45, s63, s7
	s_cselect_b32 s73, s62, s6
	v_lshl_add_u64 v[134:135], v[4:5], 2, s[46:47]
	s_add_u32 s74, s6, 0x100
	v_mov_b32_e32 v1, v0
	v_mov_b64_e32 v[6:7], v[2:3]
	v_mov_b64_e32 v[10:11], v[2:3]
	v_mov_b64_e32 v[22:23], v[2:3]
	v_mov_b64_e32 v[26:27], v[2:3]
	v_mov_b64_e32 v[38:39], v[2:3]
	v_mov_b64_e32 v[42:43], v[2:3]
	v_mov_b64_e32 v[54:55], v[2:3]
	v_mov_b64_e32 v[58:59], v[2:3]
	v_mov_b64_e32 v[14:15], v[2:3]
	v_mov_b64_e32 v[18:19], v[2:3]
	v_mov_b64_e32 v[30:31], v[2:3]
	v_mov_b64_e32 v[34:35], v[2:3]
	v_mov_b64_e32 v[46:47], v[2:3]
	v_mov_b64_e32 v[50:51], v[2:3]
	v_mov_b64_e32 v[62:63], v[2:3]
	v_mov_b64_e32 v[66:67], v[2:3]
	v_mov_b64_e32 v[70:71], v[2:3]
	v_mov_b64_e32 v[74:75], v[2:3]
	v_mov_b64_e32 v[86:87], v[2:3]
	v_mov_b64_e32 v[90:91], v[2:3]
	v_mov_b64_e32 v[102:103], v[2:3]
	v_mov_b64_e32 v[106:107], v[2:3]
	v_mov_b64_e32 v[118:119], v[2:3]
	v_mov_b64_e32 v[126:127], v[2:3]
	v_mov_b64_e32 v[78:79], v[2:3]
	v_mov_b64_e32 v[82:83], v[2:3]
	v_mov_b64_e32 v[94:95], v[2:3]
	v_mov_b64_e32 v[98:99], v[2:3]
	v_mov_b64_e32 v[110:111], v[2:3]
	v_mov_b64_e32 v[114:115], v[2:3]
	v_mov_b64_e32 v[142:143], v[2:3]
	v_mov_b64_e32 v[146:147], v[2:3]
	v_lshl_add_u64 v[138:139], s[66:67], 0, v[156:157]
	v_lshl_add_u64 v[164:165], s[66:67], 0, v[158:159]
	s_addc_u32 s75, s7, 0
	s_mov_b32 s76, -2
	s_mov_b64 s[70:71], 0
	v_mov_b64_e32 v[4:5], v[0:1]
	v_mov_b64_e32 v[8:9], v[0:1]
	v_mov_b64_e32 v[20:21], v[0:1]
	v_mov_b64_e32 v[24:25], v[0:1]
	v_mov_b64_e32 v[36:37], v[0:1]
	v_mov_b64_e32 v[40:41], v[0:1]
	v_mov_b64_e32 v[52:53], v[0:1]
	v_mov_b64_e32 v[56:57], v[0:1]
	v_mov_b64_e32 v[12:13], v[0:1]
	v_mov_b64_e32 v[16:17], v[0:1]
	v_mov_b64_e32 v[28:29], v[0:1]
	v_mov_b64_e32 v[32:33], v[0:1]
	v_mov_b64_e32 v[44:45], v[0:1]
	v_mov_b64_e32 v[48:49], v[0:1]
	v_mov_b64_e32 v[60:61], v[0:1]
	v_mov_b64_e32 v[64:65], v[0:1]
	v_mov_b64_e32 v[68:69], v[0:1]
	v_mov_b64_e32 v[72:73], v[0:1]
	v_mov_b64_e32 v[84:85], v[0:1]
	v_mov_b64_e32 v[88:89], v[0:1]
	v_mov_b64_e32 v[100:101], v[0:1]
	v_mov_b64_e32 v[104:105], v[0:1]
	v_mov_b64_e32 v[116:117], v[0:1]
	v_mov_b64_e32 v[124:125], v[0:1]
	v_mov_b64_e32 v[76:77], v[0:1]
	v_mov_b64_e32 v[80:81], v[0:1]
	v_mov_b64_e32 v[92:93], v[0:1]
	v_mov_b64_e32 v[96:97], v[0:1]
	v_mov_b64_e32 v[108:109], v[0:1]
	v_mov_b64_e32 v[112:113], v[0:1]
	v_mov_b64_e32 v[140:141], v[0:1]
	v_mov_b64_e32 v[144:145], v[0:1]
	s_branch .LBB0_899
	s_branch .Lpagefit_4
; template <class Epi, class Sched, bool ALIGN_EPI = false, bool SP2 = false>
; __device__ __forceinline__ void gemm_phase(PG8_LAS unsigned char* lds, const Gemm g, const Sched S, const Epi E) {
;     ...
;     for (;;) {
;         const bool has_next = S.next(ui + 1, nxt);
;         const char* nA = has_next ? (const char*)g.A + (size_t)nxt.pm * tstep : cA; const char* nB = has_next ? (const char*)g.Bt + (size_t)nxt.pn * tstep : cB;
;         for (int t = 0; t < nt; t += 2) {
	s_nop 0
	s_nop 0
	s_nop 0
	s_nop 0
	s_nop 0
	s_nop 0
	s_nop 0
	s_nop 0
	s_nop 0
	s_nop 0
	s_nop 0
	s_nop 0
	s_nop 0
	s_nop 0
	s_nop 0
	s_nop 0
	s_nop 0
	s_nop 0
	s_nop 0
	s_nop 0
	s_nop 0
	s_nop 0
	s_nop 0
	s_nop 0
	s_nop 0
	s_nop 0
	s_nop 0
	s_nop 0
	s_nop 0
	s_nop 0
	s_nop 0
	s_nop 0
	s_nop 0
	s_nop 0
	s_nop 0
	s_nop 0
	s_nop 0
	s_nop 0
	s_nop 0
	s_nop 0
	s_nop 0
	s_nop 0
	s_nop 0
	s_nop 0
	s_nop 0
	s_nop 0
	s_nop 0
	s_nop 0
	s_nop 0
	s_nop 0
	s_nop 0
	s_nop 0
	s_nop 0
	s_nop 0
	s_nop 0
	s_nop 0
	s_nop 0
	s_nop 0
	s_nop 0
	s_nop 0
	s_nop 0
	s_nop 0
	s_nop 0
	s_nop 0
	s_nop 0
	s_nop 0
	s_nop 0
	s_nop 0
	s_nop 0
	s_nop 0
	s_nop 0
	s_nop 0
	s_nop 0
	s_nop 0
	s_nop 0
	s_nop 0
	s_nop 0
	s_nop 0
	s_nop 0
	s_nop 0
	s_nop 0
	s_nop 0
	s_nop 0
	s_nop 0
	s_nop 0
	s_nop 0
	s_nop 0
	s_nop 0
	s_nop 0
	s_nop 0
	s_nop 0
	s_nop 0
	s_nop 0
	s_nop 0
	s_nop 0
	s_nop 0
	s_nop 0
	s_nop 0
	s_nop 0
	s_nop 0
	s_nop 0
	s_nop 0
	s_nop 0
	s_nop 0
	s_nop 0
	s_nop 0
	s_nop 0
	s_nop 0
	s_nop 0
	s_nop 0
	s_nop 0
	s_nop 0
	s_nop 0
	s_nop 0
	s_nop 0
	s_nop 0
	s_nop 0
	s_nop 0
	s_nop 0
	s_nop 0
	s_nop 0
	s_nop 0
	s_nop 0
	s_nop 0
	s_nop 0
	s_nop 0
	s_nop 0
	s_nop 0
	s_nop 0
	s_nop 0
	s_nop 0
	s_nop 0
	s_nop 0
	s_nop 0
	s_nop 0
	s_nop 0
	s_nop 0
	s_nop 0
	s_nop 0
	s_nop 0
	s_nop 0
	s_nop 0
	s_nop 0
	s_nop 0
	s_nop 0
	s_nop 0
	s_nop 0
	s_nop 0
	s_nop 0
	s_nop 0
	s_nop 0
	s_nop 0
	s_nop 0
	s_nop 0
	s_nop 0
	s_nop 0
	s_nop 0
	s_nop 0
	s_nop 0
	s_nop 0
	s_nop 0
	s_nop 0
	s_nop 0
	s_nop 0
	s_nop 0
	s_nop 0
	s_nop 0
	s_nop 0
	s_nop 0
	s_nop 0
	s_nop 0
	s_nop 0
	s_nop 0
	s_nop 0
	s_nop 0
	s_nop 0
	s_nop 0
	s_nop 0
	s_nop 0
	s_nop 0
	s_nop 0
	s_nop 0
	s_nop 0
	s_nop 0
	s_nop 0
	s_nop 0
	s_nop 0
	s_nop 0
	s_nop 0
	s_nop 0
	s_nop 0
	s_nop 0
	s_nop 0
	s_nop 0
	s_nop 0
	s_nop 0
	s_nop 0
	s_nop 0
	s_nop 0
	s_nop 0
	s_nop 0
	s_nop 0
	s_nop 0
	s_nop 0
	s_nop 0
	s_nop 0
	s_nop 0
	s_nop 0
	s_nop 0
	s_nop 0
	s_nop 0
	s_nop 0
	s_nop 0
	s_nop 0
	s_nop 0
	s_nop 0
	s_nop 0
	s_nop 0
	s_nop 0
	s_nop 0
	s_nop 0
	s_nop 0
	s_nop 0
	s_nop 0
	s_nop 0
	s_nop 0
	s_nop 0
	s_nop 0
	s_nop 0
	s_nop 0
	s_nop 0
	s_nop 0
	s_nop 0
	s_nop 0
	s_nop 0
	s_nop 0
	s_nop 0
	s_nop 0
	s_nop 0
	s_nop 0
	s_nop 0
	s_nop 0
	s_nop 0
	s_nop 0
	s_nop 0
	s_nop 0
	s_nop 0
	s_nop 0
	s_nop 0
	s_nop 0
	s_nop 0
	s_nop 0
	s_nop 0
	s_nop 0
	s_nop 0
	s_nop 0
	s_nop 0
	s_nop 0
	s_nop 0
	s_nop 0
	s_nop 0
	s_nop 0
	s_nop 0
	s_nop 0
	s_nop 0
	s_nop 0
	s_nop 0
	s_nop 0
	s_nop 0
	s_nop 0
	s_nop 0
	s_nop 0
	s_nop 0
	s_nop 0
	s_nop 0
	s_nop 0
	s_nop 0
	s_nop 0
	s_nop 0
	s_nop 0
	s_nop 0
	s_nop 0
	s_nop 0
	s_nop 0
	s_nop 0
	s_nop 0
	s_nop 0
	s_nop 0
	s_nop 0
	s_nop 0
	s_nop 0
	s_nop 0
	s_nop 0
	s_nop 0
	s_nop 0
	s_nop 0
	s_nop 0
	s_nop 0
	s_nop 0
	s_nop 0
	s_nop 0
	s_nop 0
	s_nop 0
	s_nop 0
	s_nop 0
	s_nop 0
	s_nop 0
	s_nop 0
	s_nop 0
	s_nop 0
	s_nop 0
	s_nop 0
	s_nop 0
	s_nop 0
	s_nop 0
	s_nop 0
	s_nop 0
	s_nop 0
	s_nop 0
	s_nop 0
	s_nop 0
	s_nop 0
	s_nop 0
	s_nop 0
	s_nop 0
	s_nop 0
	s_nop 0
	s_nop 0
	s_nop 0
	s_nop 0
	s_nop 0
	s_nop 0
	s_nop 0
	s_nop 0
	s_nop 0
	s_nop 0
	s_nop 0
	s_nop 0
	s_nop 0
	s_nop 0
	s_nop 0
	s_nop 0
	s_nop 0
	s_nop 0
	s_nop 0
	s_nop 0
	s_nop 0
	s_nop 0
	s_nop 0
	s_nop 0
	s_nop 0
	s_nop 0
	s_nop 0
	s_nop 0
	s_nop 0
	s_nop 0
	s_nop 0
	s_nop 0
	s_nop 0
	s_nop 0
	s_nop 0
	s_nop 0
	s_nop 0
	s_nop 0
	s_nop 0
	s_nop 0
	s_nop 0
	s_nop 0
	s_nop 0
	s_nop 0
	s_nop 0
	s_nop 0
	s_nop 0
	s_nop 0
	s_nop 0
	s_nop 0
	s_nop 0
	s_nop 0
	s_nop 0
	s_nop 0
	s_nop 0
	s_nop 0
	s_nop 0
	s_nop 0
	s_nop 0
	s_nop 0
	s_nop 0
	s_nop 0
	s_nop 0
	s_nop 0
	s_nop 0
	s_nop 0
	s_nop 0
	s_nop 0
	s_nop 0
	s_nop 0
	s_nop 0
	s_nop 0
	s_nop 0
	s_nop 0
	s_nop 0
	s_nop 0
	s_nop 0
	s_nop 0
	s_nop 0
	s_nop 0
	s_nop 0
	s_nop 0
	s_nop 0
	s_nop 0
